# attention0: prio 2 from first PV MFMA (was after eb0); PV V-frag prefetch depth 4 + row-sum tree in MFMA shadow
# baseline (speedup 1.0000x reference)
; template <int MODE>
; DI void attn_phase(const AttnArgs& a, unsigned char* lds) {
;     ...
;             auto s_compute = [&](f32x16 (&sx)[2], const int kt) __attribute__((always_inline)) {
;                 const unsigned char* kb_ = kl + ((kt - kt0) % 3) * KBUF;
; #pragma unroll
;                 for (int kb = 0; kb < 2; ++kb) {
; #pragma unroll
;                     for (int i = 0; i < 16; ++i) sx[kb][i] = 0.f;
; #pragma unroll
;                     for (int ks = 0; ks < 4; ++ks) {
;                         const bf16x8 kf = *(const bf16x8*)(kb_ + (kb * 32 + pi_perm(r)) * KSTR + ks * 32 + h * 16);
;                         sx[kb] = MFMA(kf, qf[ks], sx[kb]);
;                     }
;                 }
;     ...
;                 __builtin_amdgcn_s_setprio(1);
;                 s_compute(sn, kt + 1);
;                 f32x2 ps2 = {0.f, 0.f};
; #pragma unroll
;                 for (int kb = 0; kb < 2; ++kb)
; #pragma unroll
;                     for (int i = 0; i < 16; i += 2) {
;                         f32x2 pv = {__builtin_amdgcn_exp2f(s[kb][i] - mrow), __builtin_amdgcn_exp2f(s[kb][i + 1] - mrow)};
;                         s[kb][i] = pv.x; s[kb][i + 1] = pv.y; ps2 += pv;
;                     }
;                 lsum += ps2.x + ps2.y;
;                 bf16x8 pf[2][2];
; #pragma unroll
;                 for (int kb = 0; kb < 2; ++kb)
; #pragma unroll
;                     for (int s2 = 0; s2 < 2; ++s2) {
;                         u32x4 u;
;                         u.x = pk_bf16(s[kb][8 * s2 + 0], s[kb][8 * s2 + 1]); u.y = pk_bf16(s[kb][8 * s2 + 2], s[kb][8 * s2 + 3]);
;                         u.z = pk_bf16(s[kb][8 * s2 + 4], s[kb][8 * s2 + 5]); u.w = pk_bf16(s[kb][8 * s2 + 6], s[kb][8 * s2 + 7]);
;                         pf[kb][s2] = __builtin_bit_cast(bf16x8, u);
;                     }
;                 const unsigned char* vb_ = vl + ((kt - kt0) & 1) * VBUF;
; #pragma unroll
;                 for (int eb = 0; eb < EB; ++eb) {
; #pragma unroll
;                     for (int kb = 0; kb < 2; ++kb)
; #pragma unroll
;                         for (int s2 = 0; s2 < 2; ++s2) {
;                             const bf16x8 vf = *(const bf16x8*)(vb_ + (eb * 32 + r) * VSTR + (kb * 32 + 16 * s2 + 8 * h) * 2);
;                             O[eb] = MFMA(vf, pf[kb][s2], O[eb]);
;                         }
;                 }
;                 __builtin_amdgcn_s_setprio(0);
.LBB0_158:
	s_mul_hi_u32 s4, s72, 0xaaaaaaab
	s_lshr_b32 s74, s4, 1
	s_mul_hi_u32 s4, s24, 0xaaaaaaab
	s_lshr_b32 s4, s4, 1
	s_mulk_i32 s4, 0x6c00
	s_mulk_i32 s74, 0x6c00
	v_subrev_u32_e32 v98, s4, v210
	s_setprio 1
	v_add_u32_e32 v224, s25, v1
	v_add_u32_e32 v225, v224, v98
	ds_read_b128 v[98:101], v225 offset:9216
	ds_read_b128 v[102:105], v225 offset:9248
	v_sub_f32_e32 v66, v66, v222
	v_sub_f32_e32 v67, v67, v222
	v_sub_f32_e32 v68, v68, v222
	s_waitcnt lgkmcnt(1)
	v_mfma_f32_32x32x16_bf16 v[114:129], v[98:101], v[130:133], 0
	v_sub_f32_e32 v69, v69, v222
	v_sub_f32_e32 v70, v70, v222
	v_sub_f32_e32 v71, v71, v222
	v_sub_f32_e32 v72, v72, v222
	v_sub_f32_e32 v73, v73, v222
	v_exp_f32_e32 v66, v66
	v_exp_f32_e32 v67, v67
	s_waitcnt lgkmcnt(0)
	v_mfma_f32_32x32x16_bf16 v[114:129], v[102:105], v[138:141], v[114:129]
	ds_read_b128 v[98:101], v225 offset:9280
	ds_read_b128 v[102:105], v225 offset:9312
	v_exp_f32_e32 v68, v68
	v_exp_f32_e32 v69, v69
	v_exp_f32_e32 v70, v70
	v_exp_f32_e32 v71, v71
	v_exp_f32_e32 v72, v72
	v_exp_f32_e32 v73, v73
	s_waitcnt lgkmcnt(1)
	v_mfma_f32_32x32x16_bf16 v[114:129], v[98:101], v[142:145], v[114:129]
	ds_read_b128 v[98:101], v225 offset:13824
	ds_read_b128 v[226:229], v225 offset:13856
	v_sub_f32_e32 v74, v74, v222
	v_sub_f32_e32 v75, v75, v222
	v_sub_f32_e32 v76, v76, v222
	v_sub_f32_e32 v77, v77, v222
	v_sub_f32_e32 v78, v78, v222
	v_sub_f32_e32 v79, v79, v222
	s_waitcnt lgkmcnt(2)
	v_mfma_f32_32x32x16_bf16 v[114:129], v[102:105], v[134:137], v[114:129]
	v_sub_f32_e32 v80, v80, v222
	v_sub_f32_e32 v81, v81, v222
	v_exp_f32_e32 v74, v74
	v_exp_f32_e32 v75, v75
	v_exp_f32_e32 v76, v76
	v_exp_f32_e32 v77, v77
	v_exp_f32_e32 v78, v78
	s_waitcnt lgkmcnt(1)
	v_mfma_f32_32x32x16_bf16 v[98:113], v[98:101], v[130:133], 0
	v_exp_f32_e32 v79, v79
	v_exp_f32_e32 v80, v80
	v_exp_f32_e32 v81, v81
	v_sub_f32_e32 v82, v82, v222
	v_sub_f32_e32 v83, v83, v222
	v_sub_f32_e32 v84, v84, v222
	v_sub_f32_e32 v85, v85, v222
	s_waitcnt lgkmcnt(0)
	v_mfma_f32_32x32x16_bf16 v[98:113], v[226:229], v[138:141], v[98:113]
	ds_read_b128 v[226:229], v225 offset:13888
	ds_read_b128 v[230:233], v225 offset:13920
	ds_read_b128 v[234:237], v217 offset:27680
	ds_read_b128 v[238:241], v217 offset:27712
	ds_read_b128 v[242:245], v217 offset:27744
	v_sub_f32_e32 v86, v86, v222
	v_sub_f32_e32 v87, v87, v222
	v_sub_f32_e32 v88, v88, v222
	s_waitcnt lgkmcnt(4)
	v_mfma_f32_32x32x16_bf16 v[98:113], v[226:229], v[142:145], v[98:113]
	ds_read_b128 v[226:229], v217 offset:27648
	v_sub_f32_e32 v89, v89, v222
	v_exp_f32_e32 v82, v82
	v_exp_f32_e32 v83, v83
	v_exp_f32_e32 v84, v84
	v_exp_f32_e32 v85, v85
	v_exp_f32_e32 v86, v86
	s_waitcnt lgkmcnt(4)
	v_mfma_f32_32x32x16_bf16 v[98:113], v[230:233], v[134:137], v[98:113]
	v_cvt_pk_bf16_f32 v230, v66, v67
	v_cvt_pk_bf16_f32 v231, v68, v69
	v_cvt_pk_bf16_f32 v232, v70, v71
	v_cvt_pk_bf16_f32 v233, v72, v73
	v_exp_f32_e32 v87, v87
	v_exp_f32_e32 v88, v88
	v_exp_f32_e32 v89, v89
	s_setprio 2
	s_waitcnt lgkmcnt(0)
	v_mfma_f32_32x32x16_bf16 v[50:65], v[226:229], v[230:233], v[50:65]
	v_cvt_pk_bf16_f32 v226, v74, v75
	v_cvt_pk_bf16_f32 v227, v76, v77
	v_cvt_pk_bf16_f32 v228, v78, v79
	v_cvt_pk_bf16_f32 v229, v80, v81
	v_sub_f32_e32 v90, v90, v222
	v_sub_f32_e32 v91, v91, v222
	v_sub_f32_e32 v92, v92, v222
	v_mfma_f32_32x32x16_bf16 v[50:65], v[234:237], v[226:229], v[50:65]
	v_cvt_pk_bf16_f32 v234, v82, v83
	v_cvt_pk_bf16_f32 v235, v84, v85
	v_cvt_pk_bf16_f32 v236, v86, v87
	v_cvt_pk_bf16_f32 v237, v88, v89
	v_sub_f32_e32 v93, v93, v222
	v_sub_f32_e32 v94, v94, v222
	v_sub_f32_e32 v95, v95, v222
	v_mfma_f32_32x32x16_bf16 v[50:65], v[238:241], v[234:237], v[50:65]
	v_sub_f32_e32 v96, v96, v222
	v_sub_f32_e32 v97, v97, v222
	v_exp_f32_e32 v90, v90
	v_exp_f32_e32 v91, v91
	v_exp_f32_e32 v92, v92
	v_exp_f32_e32 v93, v93
	v_exp_f32_e32 v94, v94
	v_exp_f32_e32 v95, v95
	v_exp_f32_e32 v96, v96
	v_exp_f32_e32 v97, v97
	v_cvt_pk_bf16_f32 v238, v90, v91
	v_cvt_pk_bf16_f32 v239, v92, v93
	v_cvt_pk_bf16_f32 v240, v94, v95
	v_cvt_pk_bf16_f32 v241, v96, v97
	s_nop 1
	v_mfma_f32_32x32x16_bf16 v[50:65], v[242:245], v[238:241], v[50:65]
	ds_read_b128 v[242:245], v217 offset:32256
	ds_read_b128 v[246:249], v217 offset:32288
	v_pk_add_f32 v[66:67], v[66:67], v[82:83]
	v_pk_add_f32 v[68:69], v[68:69], v[84:85]
	v_pk_add_f32 v[70:71], v[70:71], v[86:87]
	v_pk_add_f32 v[72:73], v[72:73], v[88:89]
	v_pk_add_f32 v[74:75], v[74:75], v[90:91]
	v_pk_add_f32 v[76:77], v[76:77], v[92:93]
	v_pk_add_f32 v[78:79], v[78:79], v[94:95]
	v_pk_add_f32 v[80:81], v[80:81], v[96:97]
	ds_read_b128 v[82:85], v217 offset:32320
	ds_read_b128 v[86:89], v217 offset:32352
	ds_read_b128 v[90:93], v217 offset:36864
	ds_read_b128 v[94:97], v217 offset:36896
	s_waitcnt lgkmcnt(5)
	v_mfma_f32_32x32x16_bf16 v[34:49], v[242:245], v[230:233], v[34:49]
	v_pk_add_f32 v[66:67], v[66:67], v[74:75]
	v_pk_add_f32 v[68:69], v[68:69], v[76:77]
	v_pk_add_f32 v[70:71], v[70:71], v[78:79]
	v_pk_add_f32 v[72:73], v[72:73], v[80:81]
	s_waitcnt lgkmcnt(4)
	v_mfma_f32_32x32x16_bf16 v[34:49], v[246:249], v[226:229], v[34:49]
	ds_read_b128 v[74:77], v217 offset:36928
	ds_read_b128 v[78:81], v217 offset:36960
	v_pk_add_f32 v[66:67], v[66:67], v[70:71]
	v_pk_add_f32 v[68:69], v[68:69], v[72:73]
	s_waitcnt lgkmcnt(5)
	v_mfma_f32_32x32x16_bf16 v[34:49], v[82:85], v[234:237], v[34:49]
	v_pk_add_f32 v[66:67], v[66:67], v[68:69]
	s_waitcnt lgkmcnt(4)
	v_mfma_f32_32x32x16_bf16 v[34:49], v[86:89], v[238:241], v[34:49]
	ds_read_b128 v[242:245], v217 offset:41472
	ds_read_b128 v[246:249], v217 offset:41504
	v_add_f32_e32 v66, v66, v67
	s_waitcnt lgkmcnt(5)
	v_mfma_f32_32x32x16_bf16 v[18:33], v[90:93], v[230:233], v[18:33]
	v_add_f32_e32 v219, v219, v66
	s_waitcnt lgkmcnt(4)
	v_mfma_f32_32x32x16_bf16 v[18:33], v[94:97], v[226:229], v[18:33]
	ds_read_b128 v[82:85], v217 offset:41536
	ds_read_b128 v[86:89], v217 offset:41568
	s_waitcnt lgkmcnt(5)
	v_mfma_f32_32x32x16_bf16 v[18:33], v[74:77], v[234:237], v[18:33]
	s_waitcnt lgkmcnt(4)
	v_mfma_f32_32x32x16_bf16 v[18:33], v[78:81], v[238:241], v[18:33]
	s_waitcnt lgkmcnt(3)
	v_mfma_f32_32x32x16_bf16 v[2:17], v[242:245], v[230:233], v[2:17]
	s_waitcnt lgkmcnt(2)
	v_mfma_f32_32x32x16_bf16 v[2:17], v[246:249], v[226:229], v[2:17]
	s_waitcnt lgkmcnt(1)
	v_mfma_f32_32x32x16_bf16 v[2:17], v[82:85], v[234:237], v[2:17]
	s_waitcnt lgkmcnt(0)
	v_mfma_f32_32x32x16_bf16 v[2:17], v[86:89], v[238:241], v[2:17]
	s_setprio 0
	v_cndmask_b32_e64 v225, 0, 1, s[0:1]
	v_cmp_ne_u32_e64 s[4:5], 1, v225
	s_andn2_b64 vcc, exec, s[0:1]
	s_cbranch_vccnz .LBB0_160
	v_subrev_u32_e32 v225, s74, v212
	s_add_i32 s0, s25, 0
	v_add_u32_e32 v225, s0, v225
	s_waitcnt vmcnt(1)
	ds_write_b128 v225, v[150:153] offset:18432
	s_waitcnt vmcnt(0)
	ds_write_b128 v225, v[158:161] offset:23040

; template <int MODE>
; DI void attn_phase(const AttnArgs& a, unsigned char* lds) {
;     ...
;             auto s_compute = [&](f32x16 (&sx)[2], const int kt) __attribute__((always_inline)) {
;                 const unsigned char* kb_ = kl + ((kt - kt0) % 3) * KBUF;
; #pragma unroll
;                 for (int kb = 0; kb < 2; ++kb) {
; #pragma unroll
;                     for (int i = 0; i < 16; ++i) sx[kb][i] = 0.f;
; #pragma unroll
;                     for (int ks = 0; ks < 4; ++ks) {
;                         const bf16x8 kf = *(const bf16x8*)(kb_ + (kb * 32 + pi_perm(r)) * KSTR + ks * 32 + h * 16);
;                         sx[kb] = MFMA(kf, qf[ks], sx[kb]);
;                     }
;                 }
;     ...
;                 __builtin_amdgcn_s_setprio(1);
;                 s_compute(sn, kt + 1);
;                 f32x2 ps2 = {0.f, 0.f};
; #pragma unroll
;                 for (int kb = 0; kb < 2; ++kb)
; #pragma unroll
;                     for (int i = 0; i < 16; i += 2) {
;                         f32x2 pv = {__builtin_amdgcn_exp2f(s[kb][i] - mrow), __builtin_amdgcn_exp2f(s[kb][i + 1] - mrow)};
;                         s[kb][i] = pv.x; s[kb][i + 1] = pv.y; ps2 += pv;
;                     }
;                 lsum += ps2.x + ps2.y;
;                 bf16x8 pf[2][2];
; #pragma unroll
;                 for (int kb = 0; kb < 2; ++kb)
; #pragma unroll
;                     for (int s2 = 0; s2 < 2; ++s2) {
;                         u32x4 u;
;                         u.x = pk_bf16(s[kb][8 * s2 + 0], s[kb][8 * s2 + 1]); u.y = pk_bf16(s[kb][8 * s2 + 2], s[kb][8 * s2 + 3]);
;                         u.z = pk_bf16(s[kb][8 * s2 + 4], s[kb][8 * s2 + 5]); u.w = pk_bf16(s[kb][8 * s2 + 6], s[kb][8 * s2 + 7]);
;                         pf[kb][s2] = __builtin_bit_cast(bf16x8, u);
;                     }
;                 const unsigned char* vb_ = vl + ((kt - kt0) & 1) * VBUF;
; #pragma unroll
;                 for (int eb = 0; eb < EB; ++eb) {
; #pragma unroll
;                     for (int kb = 0; kb < 2; ++kb)
; #pragma unroll
;                         for (int s2 = 0; s2 < 2; ++s2) {
;                             const bf16x8 vf = *(const bf16x8*)(vb_ + (eb * 32 + r) * VSTR + (kb * 32 + 16 * s2 + 8 * h) * 2);
;                             O[eb] = MFMA(vf, pf[kb][s2], O[eb]);
;                         }
;                 }
;                 __builtin_amdgcn_s_setprio(0);
.LBB0_169:
	v_subrev_u32_e32 v66, s74, v213
	s_setprio 1
	v_add_u32_e32 v223, v224, v66
	ds_read_b128 v[66:69], v223
	ds_read_b128 v[82:85], v223 offset:32
	v_sub_f32_e32 v114, v114, v222
	v_sub_f32_e32 v115, v115, v222
	v_sub_f32_e32 v116, v116, v222
	s_waitcnt lgkmcnt(1)
	v_mfma_f32_32x32x16_bf16 v[66:81], v[66:69], v[130:133], 0
	v_sub_f32_e32 v117, v117, v222
	v_sub_f32_e32 v118, v118, v222
	v_sub_f32_e32 v119, v119, v222
	v_sub_f32_e32 v120, v120, v222
	v_sub_f32_e32 v121, v121, v222
	v_exp_f32_e32 v114, v114
	v_exp_f32_e32 v115, v115
	s_waitcnt lgkmcnt(0)
	v_mfma_f32_32x32x16_bf16 v[66:81], v[82:85], v[138:141], v[66:81]
	ds_read_b128 v[82:85], v223 offset:64
	ds_read_b128 v[86:89], v223 offset:96
	v_exp_f32_e32 v116, v116
	v_exp_f32_e32 v117, v117
	v_exp_f32_e32 v118, v118
	v_exp_f32_e32 v119, v119
	v_exp_f32_e32 v120, v120
	v_exp_f32_e32 v121, v121
	s_waitcnt lgkmcnt(1)
	v_mfma_f32_32x32x16_bf16 v[66:81], v[82:85], v[142:145], v[66:81]
	ds_read_b128 v[82:85], v223 offset:4608
	ds_read_b128 v[224:227], v223 offset:4640
	v_sub_f32_e32 v122, v122, v222
	v_sub_f32_e32 v123, v123, v222
	v_sub_f32_e32 v124, v124, v222
	v_sub_f32_e32 v125, v125, v222
	v_sub_f32_e32 v126, v126, v222
	v_sub_f32_e32 v127, v127, v222
	s_waitcnt lgkmcnt(2)
	v_mfma_f32_32x32x16_bf16 v[66:81], v[86:89], v[134:137], v[66:81]
	v_sub_f32_e32 v128, v128, v222
	v_sub_f32_e32 v129, v129, v222
	v_exp_f32_e32 v122, v122
	v_exp_f32_e32 v123, v123
	v_exp_f32_e32 v124, v124
	v_exp_f32_e32 v125, v125
	v_exp_f32_e32 v126, v126
	s_waitcnt lgkmcnt(1)
	v_mfma_f32_32x32x16_bf16 v[82:97], v[82:85], v[130:133], 0
	v_exp_f32_e32 v127, v127
	v_exp_f32_e32 v128, v128
	v_exp_f32_e32 v129, v129
	v_sub_f32_e32 v98, v98, v222
	v_sub_f32_e32 v99, v99, v222
	v_sub_f32_e32 v100, v100, v222
	v_sub_f32_e32 v101, v101, v222
	s_waitcnt lgkmcnt(0)
	v_mfma_f32_32x32x16_bf16 v[82:97], v[224:227], v[138:141], v[82:97]
	ds_read_b128 v[224:227], v223 offset:4672
	ds_read_b128 v[228:231], v223 offset:4704
	ds_read_b128 v[232:235], v217 offset:46112
	ds_read_b128 v[236:239], v217 offset:46144
	ds_read_b128 v[240:243], v217 offset:46176
	v_sub_f32_e32 v102, v102, v222
	v_sub_f32_e32 v103, v103, v222
	v_sub_f32_e32 v104, v104, v222
	s_waitcnt lgkmcnt(4)
	v_mfma_f32_32x32x16_bf16 v[82:97], v[224:227], v[142:145], v[82:97]
	ds_read_b128 v[224:227], v217 offset:46080
	v_sub_f32_e32 v105, v105, v222
	v_exp_f32_e32 v98, v98
	v_exp_f32_e32 v99, v99
	v_exp_f32_e32 v100, v100
	v_exp_f32_e32 v101, v101
	v_exp_f32_e32 v102, v102
	s_waitcnt lgkmcnt(4)
	v_mfma_f32_32x32x16_bf16 v[82:97], v[228:231], v[134:137], v[82:97]
	v_cvt_pk_bf16_f32 v228, v114, v115
	v_cvt_pk_bf16_f32 v229, v116, v117
	v_cvt_pk_bf16_f32 v230, v118, v119
	v_cvt_pk_bf16_f32 v231, v120, v121
	v_exp_f32_e32 v103, v103
	v_exp_f32_e32 v104, v104
	v_exp_f32_e32 v105, v105
	s_setprio 2
	s_waitcnt lgkmcnt(0)
	v_mfma_f32_32x32x16_bf16 v[50:65], v[224:227], v[228:231], v[50:65]
	v_cvt_pk_bf16_f32 v224, v122, v123
	v_cvt_pk_bf16_f32 v225, v124, v125
	v_cvt_pk_bf16_f32 v226, v126, v127
	v_cvt_pk_bf16_f32 v227, v128, v129
	v_sub_f32_e32 v106, v106, v222
	v_sub_f32_e32 v107, v107, v222
	v_sub_f32_e32 v108, v108, v222
	v_mfma_f32_32x32x16_bf16 v[50:65], v[232:235], v[224:227], v[50:65]
	v_cvt_pk_bf16_f32 v232, v98, v99
	v_cvt_pk_bf16_f32 v233, v100, v101
	v_cvt_pk_bf16_f32 v234, v102, v103
	v_cvt_pk_bf16_f32 v235, v104, v105
	v_sub_f32_e32 v109, v109, v222
	v_sub_f32_e32 v110, v110, v222
	v_sub_f32_e32 v111, v111, v222
	v_mfma_f32_32x32x16_bf16 v[50:65], v[236:239], v[232:235], v[50:65]
	v_sub_f32_e32 v112, v112, v222
	v_sub_f32_e32 v113, v113, v222
	v_exp_f32_e32 v106, v106
	v_exp_f32_e32 v107, v107
	v_exp_f32_e32 v108, v108
	v_exp_f32_e32 v109, v109
	v_exp_f32_e32 v110, v110
	v_exp_f32_e32 v111, v111
	v_exp_f32_e32 v112, v112
	v_exp_f32_e32 v113, v113
	v_cvt_pk_bf16_f32 v236, v106, v107
	v_cvt_pk_bf16_f32 v237, v108, v109
	v_cvt_pk_bf16_f32 v238, v110, v111
	v_cvt_pk_bf16_f32 v239, v112, v113
	s_nop 1
	v_mfma_f32_32x32x16_bf16 v[50:65], v[240:243], v[236:239], v[50:65]
	ds_read_b128 v[240:243], v217 offset:50688
	ds_read_b128 v[244:247], v217 offset:50720
	v_pk_add_f32 v[98:99], v[98:99], v[114:115]
	v_pk_add_f32 v[100:101], v[100:101], v[116:117]
	v_pk_add_f32 v[102:103], v[102:103], v[118:119]
	v_pk_add_f32 v[104:105], v[104:105], v[120:121]
	v_pk_add_f32 v[106:107], v[106:107], v[122:123]
	v_pk_add_f32 v[108:109], v[108:109], v[124:125]
	v_pk_add_f32 v[110:111], v[110:111], v[126:127]
	v_pk_add_f32 v[112:113], v[112:113], v[128:129]
	ds_read_b128 v[114:117], v217 offset:50752
	ds_read_b128 v[118:121], v217 offset:50784
	ds_read_b128 v[122:125], v217 offset:55296
	ds_read_b128 v[126:129], v217 offset:55328
	s_waitcnt lgkmcnt(5)
	v_mfma_f32_32x32x16_bf16 v[34:49], v[240:243], v[228:231], v[34:49]
	v_pk_add_f32 v[98:99], v[98:99], v[106:107]
	v_pk_add_f32 v[100:101], v[100:101], v[108:109]
	v_pk_add_f32 v[102:103], v[102:103], v[110:111]
	v_pk_add_f32 v[104:105], v[104:105], v[112:113]
	s_waitcnt lgkmcnt(4)
	v_mfma_f32_32x32x16_bf16 v[34:49], v[244:247], v[224:227], v[34:49]
	ds_read_b128 v[106:109], v217 offset:55360
	ds_read_b128 v[110:113], v217 offset:55392
	v_pk_add_f32 v[98:99], v[98:99], v[102:103]
	v_pk_add_f32 v[100:101], v[100:101], v[104:105]
	s_waitcnt lgkmcnt(5)
	v_mfma_f32_32x32x16_bf16 v[34:49], v[114:117], v[232:235], v[34:49]
	v_pk_add_f32 v[98:99], v[98:99], v[100:101]
	s_waitcnt lgkmcnt(4)
	v_mfma_f32_32x32x16_bf16 v[34:49], v[118:121], v[236:239], v[34:49]
	ds_read_b128 v[240:243], v217 offset:59904
	ds_read_b128 v[244:247], v217 offset:59936
	v_add_f32_e32 v98, v98, v99
	s_waitcnt lgkmcnt(5)
	v_mfma_f32_32x32x16_bf16 v[18:33], v[122:125], v[228:231], v[18:33]
	v_add_f32_e32 v219, v219, v98
	s_waitcnt lgkmcnt(4)
	v_mfma_f32_32x32x16_bf16 v[18:33], v[126:129], v[224:227], v[18:33]
	ds_read_b128 v[114:117], v217 offset:59968
	ds_read_b128 v[118:121], v217 offset:60000
	s_waitcnt lgkmcnt(5)
	v_mfma_f32_32x32x16_bf16 v[18:33], v[106:109], v[232:235], v[18:33]
	s_waitcnt lgkmcnt(4)
	v_mfma_f32_32x32x16_bf16 v[18:33], v[110:113], v[236:239], v[18:33]
	s_waitcnt lgkmcnt(3)
	v_mfma_f32_32x32x16_bf16 v[2:17], v[240:243], v[228:231], v[2:17]
	s_waitcnt lgkmcnt(2)
	v_mfma_f32_32x32x16_bf16 v[2:17], v[244:247], v[224:227], v[2:17]
	s_waitcnt lgkmcnt(1)
	v_mfma_f32_32x32x16_bf16 v[2:17], v[114:117], v[232:235], v[2:17]
	s_waitcnt lgkmcnt(0)
	v_mfma_f32_32x32x16_bf16 v[2:17], v[118:121], v[236:239], v[2:17]
	s_setprio 0
	s_andn2_b64 vcc, exec, s[0:1]
	s_cbranch_vccnz .LBB0_171
	s_mul_hi_u32 s0, s40, 0xaaaaaaab
	s_lshr_b32 s0, s0, 1
	s_mulk_i32 s0, 0x6c00
	v_subrev_u32_e32 v223, s0, v212
	s_add_i32 s0, s25, 0
	v_add_u32_e32 v223, s0, v223
	s_waitcnt vmcnt(1)
	ds_write_b128 v223, v[150:153] offset:27648
	s_waitcnt vmcnt(0)
	ds_write_b128 v223, v[158:161] offset:32256
